# SEL attention: K/V prefetch really overlapped (Q waited before prefetch, list-entry loads deferred), windowed list lookup, 16-byte partial stores via permlane16 swap; OWN stores widened likewise
# speedup vs baseline: 1.0105x; 1.0105x over previous
.Lown_noq:
	v_div_scale_f32 v116, s[8:9], v120, v120, 1.0
	v_rcp_f32_e32 v117, v116
	v_div_scale_f32 v118, vcc, 1.0, v120, 1.0
	s_mov_b32 s67, s51
	v_fma_f32 v119, -v116, v117, 1.0
	v_fmac_f32_e32 v117, v119, v117
	v_mul_f32_e32 v119, v118, v117
	v_fma_f32 v121, -v116, v119, v118
	v_fmac_f32_e32 v119, v121, v117
	v_fma_f32 v116, -v116, v119, v118
	v_div_fmas_f32 v116, v116, v117, v119
	v_div_fixup_f32 v118, v116, v120, 1.0
	v_mad_i64_i32 v[116:117], s[8:9], v231, 24, 0
	v_or_b32_e32 v116, s48, v116
	v_lshlrev_b64 v[116:117], 8, v[116:117]
	v_lshl_add_u64 v[116:117], v[186:187], 0, v[116:117]
	v_and_b32_e32 v119, 16, v197
	v_lshrrev_b32_e32 v121, 1, v119
	v_add_u32_e32 v119, v119, v121
	v_add_co_u32_e32 v116, vcc, v116, v119
	s_nop 1
	v_addc_co_u32_e32 v117, vcc, 0, v117, vcc
	v_mul_f32_e32 v84, v84, v118
	v_mul_f32_e32 v85, v85, v118
	v_mul_f32_e32 v86, v86, v118
	v_mul_f32_e32 v87, v87, v118
	v_mul_f32_e32 v88, v88, v118
	v_mul_f32_e32 v89, v89, v118
	v_mul_f32_e32 v90, v90, v118
	v_mul_f32_e32 v91, v91, v118
	v_mul_f32_e32 v92, v92, v118
	v_mul_f32_e32 v93, v93, v118
	v_mul_f32_e32 v94, v94, v118
	v_mul_f32_e32 v95, v95, v118
	v_mul_f32_e32 v96, v96, v118
	v_mul_f32_e32 v97, v97, v118
	v_mul_f32_e32 v98, v98, v118
	v_mul_f32_e32 v99, v99, v118
	v_mul_f32_e32 v100, v100, v118
	v_mul_f32_e32 v101, v101, v118
	v_mul_f32_e32 v102, v102, v118
	v_mul_f32_e32 v103, v103, v118
	v_mul_f32_e32 v104, v104, v118
	v_mul_f32_e32 v105, v105, v118
	v_mul_f32_e32 v106, v106, v118
	v_mul_f32_e32 v107, v107, v118
	v_mul_f32_e32 v108, v108, v118
	v_mul_f32_e32 v109, v109, v118
	v_mul_f32_e32 v110, v110, v118
	v_mul_f32_e32 v111, v111, v118
	v_mul_f32_e32 v112, v112, v118
	v_mul_f32_e32 v113, v113, v118
	v_mul_f32_e32 v114, v114, v118
	v_mul_f32_e32 v115, v115, v118
	v_cvt_pk_bf16_f32 v112, v112, v113
	v_cvt_pk_bf16_f32 v113, v114, v115
	v_cvt_pk_bf16_f32 v114, v108, v109
	v_cvt_pk_bf16_f32 v115, v110, v111
	v_cvt_pk_bf16_f32 v104, v104, v105
	v_cvt_pk_bf16_f32 v105, v106, v107
	v_cvt_pk_bf16_f32 v106, v100, v101
	v_cvt_pk_bf16_f32 v107, v102, v103
	v_cvt_pk_bf16_f32 v96, v96, v97
	v_cvt_pk_bf16_f32 v97, v98, v99
	v_cvt_pk_bf16_f32 v98, v92, v93
	v_cvt_pk_bf16_f32 v99, v94, v95
	v_cvt_pk_bf16_f32 v88, v88, v89
	v_cvt_pk_bf16_f32 v89, v90, v91
	v_cvt_pk_bf16_f32 v90, v84, v85
	v_cvt_pk_bf16_f32 v91, v86, v87
	s_nop 1
	v_permlane16_swap_b32_e32 v112, v114
	v_permlane16_swap_b32_e32 v113, v115
	v_permlane16_swap_b32_e32 v104, v106
	v_permlane16_swap_b32_e32 v105, v107
	v_permlane16_swap_b32_e32 v96, v98
	v_permlane16_swap_b32_e32 v97, v99
	v_permlane16_swap_b32_e32 v88, v90
	v_permlane16_swap_b32_e32 v89, v91
	global_store_dwordx4 v[116:117], v[112:115], off
	global_store_dwordx4 v[116:117], v[104:107], off offset:64
	global_store_dwordx4 v[116:117], v[96:99], off offset:128
	global_store_dwordx4 v[116:117], v[88:91], off offset:192
	s_andn2_b64 vcc, exec, s[10:11]
	s_mov_b32 s48, s50
	s_mov_b32 s8, s65
	s_cbranch_vccz .LBB0_90

.Lown_ld1_done:
.LBB0_77:
	v_div_scale_f32 v148, s[68:69], v154, v154, 1.0
	v_rcp_f32_e32 v149, v148
	v_div_scale_f32 v150, vcc, 1.0, v154, 1.0
	v_fma_f32 v151, -v148, v149, 1.0
	v_fmac_f32_e32 v149, v151, v149
	v_mul_f32_e32 v151, v150, v149
	v_fma_f32 v155, -v148, v151, v150
	v_fmac_f32_e32 v151, v155, v149
	v_fma_f32 v148, -v148, v151, v150
	v_div_fmas_f32 v148, v148, v149, v151
	v_div_fixup_f32 v150, v148, v154, 1.0
	v_mad_i64_i32 v[148:149], s[68:69], v232, 24, 0
	v_or_b32_e32 v148, s48, v148
	v_lshlrev_b64 v[148:149], 8, v[148:149]
	v_lshl_add_u64 v[148:149], v[186:187], 0, v[148:149]
	v_and_b32_e32 v151, 16, v197
	v_lshrrev_b32_e32 v155, 1, v151
	v_add_u32_e32 v151, v151, v155
	v_add_co_u32_e32 v148, vcc, v148, v151
	s_nop 1
	v_addc_co_u32_e32 v149, vcc, 0, v149, vcc
	v_mul_f32_e32 v116, v116, v150
	v_mul_f32_e32 v117, v117, v150
	v_mul_f32_e32 v118, v118, v150
	v_mul_f32_e32 v119, v119, v150
	v_mul_f32_e32 v120, v120, v150
	v_mul_f32_e32 v121, v121, v150
	v_mul_f32_e32 v122, v122, v150
	v_mul_f32_e32 v123, v123, v150
	v_mul_f32_e32 v124, v124, v150
	v_mul_f32_e32 v125, v125, v150
	v_mul_f32_e32 v126, v126, v150
	v_mul_f32_e32 v127, v127, v150
	v_mul_f32_e32 v128, v128, v150
	v_mul_f32_e32 v129, v129, v150
	v_mul_f32_e32 v130, v130, v150
	v_mul_f32_e32 v131, v131, v150
	v_mul_f32_e32 v132, v132, v150
	v_mul_f32_e32 v133, v133, v150
	v_mul_f32_e32 v134, v134, v150
	v_mul_f32_e32 v135, v135, v150
	v_mul_f32_e32 v136, v136, v150
	v_mul_f32_e32 v137, v137, v150
	v_mul_f32_e32 v138, v138, v150
	v_mul_f32_e32 v139, v139, v150
	v_mul_f32_e32 v140, v140, v150
	v_mul_f32_e32 v141, v141, v150
	v_mul_f32_e32 v142, v142, v150
	v_mul_f32_e32 v143, v143, v150
	v_mul_f32_e32 v144, v144, v150
	v_mul_f32_e32 v145, v145, v150
	v_mul_f32_e32 v146, v146, v150
	v_mul_f32_e32 v147, v147, v150
	v_cvt_pk_bf16_f32 v144, v144, v145
	v_cvt_pk_bf16_f32 v145, v146, v147
	v_cvt_pk_bf16_f32 v146, v140, v141
	v_cvt_pk_bf16_f32 v147, v142, v143
	v_cvt_pk_bf16_f32 v136, v136, v137
	v_cvt_pk_bf16_f32 v137, v138, v139
	v_cvt_pk_bf16_f32 v138, v132, v133
	v_cvt_pk_bf16_f32 v139, v134, v135
	v_cvt_pk_bf16_f32 v128, v128, v129
	v_cvt_pk_bf16_f32 v129, v130, v131
	v_cvt_pk_bf16_f32 v130, v124, v125
	v_cvt_pk_bf16_f32 v131, v126, v127
	v_cvt_pk_bf16_f32 v119, v118, v119
	v_cvt_pk_bf16_f32 v118, v116, v117
	v_cvt_pk_bf16_f32 v116, v120, v121
	v_cvt_pk_bf16_f32 v117, v122, v123
	s_nop 1
	v_permlane16_swap_b32_e32 v144, v146
	v_permlane16_swap_b32_e32 v145, v147
	v_permlane16_swap_b32_e32 v136, v138
	v_permlane16_swap_b32_e32 v137, v139
	v_permlane16_swap_b32_e32 v128, v130
	v_permlane16_swap_b32_e32 v129, v131
	v_permlane16_swap_b32_e32 v116, v118
	v_permlane16_swap_b32_e32 v117, v119
	global_store_dwordx4 v[148:149], v[144:147], off
	global_store_dwordx4 v[148:149], v[136:139], off offset:64
	global_store_dwordx4 v[148:149], v[128:131], off offset:128
	global_store_dwordx4 v[148:149], v[116:119], off offset:192
	ds_bpermute_b32 v122, v152, v191
	s_and_b64 vcc, exec, s[24:25]
	s_waitcnt lgkmcnt(0)
	v_add_f32_e32 v120, v191, v122
	ds_bpermute_b32 v121, v153, v120
	s_waitcnt lgkmcnt(0)
	v_add_f32_e32 v120, v120, v121
	s_cbranch_vccz .LBB0_64
	s_waitcnt vmcnt(4)
	v_add_f32_e32 v120, v120, v233
	v_lshlrev_b32_e32 v254, 16, v0
	v_and_b32_e32 v0, 0xffff0000, v0
	v_lshlrev_b32_e32 v155, 16, v1
	v_and_b32_e32 v1, 0xffff0000, v1
	v_add_f32_e32 v112, v112, v254
	v_add_f32_e32 v113, v113, v0
	v_add_f32_e32 v114, v114, v155
	v_add_f32_e32 v115, v115, v1
	v_lshlrev_b32_e32 v254, 16, v2
	v_and_b32_e32 v2, 0xffff0000, v2
	v_lshlrev_b32_e32 v155, 16, v3
	v_and_b32_e32 v3, 0xffff0000, v3
	v_add_f32_e32 v108, v108, v254
	v_add_f32_e32 v109, v109, v2
	v_add_f32_e32 v110, v110, v155
	v_add_f32_e32 v111, v111, v3
	v_lshlrev_b32_e32 v254, 16, v4
	v_and_b32_e32 v4, 0xffff0000, v4
	v_lshlrev_b32_e32 v155, 16, v5
	v_and_b32_e32 v5, 0xffff0000, v5
	v_add_f32_e32 v104, v104, v254
	v_add_f32_e32 v105, v105, v4
	v_add_f32_e32 v106, v106, v155
	v_add_f32_e32 v107, v107, v5
	v_lshlrev_b32_e32 v254, 16, v6
	v_and_b32_e32 v6, 0xffff0000, v6
	v_lshlrev_b32_e32 v155, 16, v7
	v_and_b32_e32 v7, 0xffff0000, v7
	v_add_f32_e32 v100, v100, v254
	v_add_f32_e32 v101, v101, v6
	v_add_f32_e32 v102, v102, v155
	v_add_f32_e32 v103, v103, v7
	v_lshlrev_b32_e32 v254, 16, v8
	v_and_b32_e32 v8, 0xffff0000, v8
	v_lshlrev_b32_e32 v155, 16, v9
	v_and_b32_e32 v9, 0xffff0000, v9
	v_add_f32_e32 v96, v96, v254
	v_add_f32_e32 v97, v97, v8
	v_add_f32_e32 v98, v98, v155
	v_add_f32_e32 v99, v99, v9
	v_lshlrev_b32_e32 v254, 16, v10
	v_and_b32_e32 v10, 0xffff0000, v10
	v_lshlrev_b32_e32 v155, 16, v11
	v_and_b32_e32 v11, 0xffff0000, v11
	v_add_f32_e32 v92, v92, v254
	v_add_f32_e32 v93, v93, v10
	v_add_f32_e32 v94, v94, v155
	v_add_f32_e32 v95, v95, v11
	v_lshlrev_b32_e32 v254, 16, v12
	v_and_b32_e32 v12, 0xffff0000, v12
	v_lshlrev_b32_e32 v155, 16, v13
	v_and_b32_e32 v13, 0xffff0000, v13
	v_add_f32_e32 v88, v88, v254
	v_add_f32_e32 v89, v89, v12
	v_add_f32_e32 v90, v90, v155
	v_add_f32_e32 v91, v91, v13
	v_lshlrev_b32_e32 v254, 16, v14
	v_and_b32_e32 v14, 0xffff0000, v14
	v_lshlrev_b32_e32 v155, 16, v15
	v_and_b32_e32 v15, 0xffff0000, v15
	v_add_f32_e32 v84, v84, v254
	v_add_f32_e32 v85, v85, v14
	v_add_f32_e32 v86, v86, v155
	v_add_f32_e32 v87, v87, v15
	s_cmp_lt_u32 s58, 2
	s_cbranch_scc1 .Lown_add1_done
	v_add_f32_e32 v120, v120, v234
	v_lshlrev_b32_e32 v254, 16, v16
	v_and_b32_e32 v16, 0xffff0000, v16
	v_lshlrev_b32_e32 v155, 16, v17
	v_and_b32_e32 v17, 0xffff0000, v17
	v_add_f32_e32 v112, v112, v254
	v_add_f32_e32 v113, v113, v16
	v_add_f32_e32 v114, v114, v155
	v_add_f32_e32 v115, v115, v17
	v_lshlrev_b32_e32 v254, 16, v18
	v_and_b32_e32 v18, 0xffff0000, v18
	v_lshlrev_b32_e32 v155, 16, v19
	v_and_b32_e32 v19, 0xffff0000, v19
	v_add_f32_e32 v108, v108, v254
	v_add_f32_e32 v109, v109, v18
	v_add_f32_e32 v110, v110, v155
	v_add_f32_e32 v111, v111, v19
	v_lshlrev_b32_e32 v254, 16, v20
	v_and_b32_e32 v20, 0xffff0000, v20
	v_lshlrev_b32_e32 v155, 16, v21
	v_and_b32_e32 v21, 0xffff0000, v21
	v_add_f32_e32 v104, v104, v254
	v_add_f32_e32 v105, v105, v20
	v_add_f32_e32 v106, v106, v155
	v_add_f32_e32 v107, v107, v21
	v_lshlrev_b32_e32 v254, 16, v22
	v_and_b32_e32 v22, 0xffff0000, v22
	v_lshlrev_b32_e32 v155, 16, v23
	v_and_b32_e32 v23, 0xffff0000, v23
	v_add_f32_e32 v100, v100, v254
	v_add_f32_e32 v101, v101, v22
	v_add_f32_e32 v102, v102, v155
	v_add_f32_e32 v103, v103, v23
	v_lshlrev_b32_e32 v254, 16, v24
	v_and_b32_e32 v24, 0xffff0000, v24
	v_lshlrev_b32_e32 v155, 16, v25
	v_and_b32_e32 v25, 0xffff0000, v25
	v_add_f32_e32 v96, v96, v254
	v_add_f32_e32 v97, v97, v24
	v_add_f32_e32 v98, v98, v155
	v_add_f32_e32 v99, v99, v25
	v_lshlrev_b32_e32 v254, 16, v26
	v_and_b32_e32 v26, 0xffff0000, v26
	v_lshlrev_b32_e32 v155, 16, v27
	v_and_b32_e32 v27, 0xffff0000, v27
	v_add_f32_e32 v92, v92, v254
	v_add_f32_e32 v93, v93, v26
	v_add_f32_e32 v94, v94, v155
	v_add_f32_e32 v95, v95, v27
	v_lshlrev_b32_e32 v254, 16, v28
	v_and_b32_e32 v28, 0xffff0000, v28
	v_lshlrev_b32_e32 v155, 16, v29
	v_and_b32_e32 v29, 0xffff0000, v29
	v_add_f32_e32 v88, v88, v254
	v_add_f32_e32 v89, v89, v28
	v_add_f32_e32 v90, v90, v155
	v_add_f32_e32 v91, v91, v29
	v_lshlrev_b32_e32 v254, 16, v30
	v_and_b32_e32 v30, 0xffff0000, v30
	v_lshlrev_b32_e32 v155, 16, v31
	v_and_b32_e32 v31, 0xffff0000, v31
	v_add_f32_e32 v84, v84, v254
	v_add_f32_e32 v85, v85, v30
	v_add_f32_e32 v86, v86, v155
	v_add_f32_e32 v87, v87, v31
	s_cmp_lt_u32 s58, 3
	s_cbranch_scc1 .Lown_add1_done
	v_add_f32_e32 v120, v120, v235
	v_lshlrev_b32_e32 v254, 16, v236
	v_and_b32_e32 v236, 0xffff0000, v236
	v_lshlrev_b32_e32 v155, 16, v237
	v_and_b32_e32 v237, 0xffff0000, v237
	v_add_f32_e32 v112, v112, v254
	v_add_f32_e32 v113, v113, v236
	v_add_f32_e32 v114, v114, v155
	v_add_f32_e32 v115, v115, v237
	v_lshlrev_b32_e32 v254, 16, v238
	v_and_b32_e32 v238, 0xffff0000, v238
	v_lshlrev_b32_e32 v155, 16, v239
	v_and_b32_e32 v239, 0xffff0000, v239
	v_add_f32_e32 v108, v108, v254
	v_add_f32_e32 v109, v109, v238
	v_add_f32_e32 v110, v110, v155
	v_add_f32_e32 v111, v111, v239
	v_lshlrev_b32_e32 v254, 16, v240
	v_and_b32_e32 v240, 0xffff0000, v240
	v_lshlrev_b32_e32 v155, 16, v241
	v_and_b32_e32 v241, 0xffff0000, v241
	v_add_f32_e32 v104, v104, v254
	v_add_f32_e32 v105, v105, v240
	v_add_f32_e32 v106, v106, v155
	v_add_f32_e32 v107, v107, v241
	v_lshlrev_b32_e32 v254, 16, v242
	v_and_b32_e32 v242, 0xffff0000, v242
	v_lshlrev_b32_e32 v155, 16, v243
	v_and_b32_e32 v243, 0xffff0000, v243
	v_add_f32_e32 v100, v100, v254
	v_add_f32_e32 v101, v101, v242
	v_add_f32_e32 v102, v102, v155
	v_add_f32_e32 v103, v103, v243
	v_lshlrev_b32_e32 v254, 16, v244
	v_and_b32_e32 v244, 0xffff0000, v244
	v_lshlrev_b32_e32 v155, 16, v245
	v_and_b32_e32 v245, 0xffff0000, v245
	v_add_f32_e32 v96, v96, v254
	v_add_f32_e32 v97, v97, v244
	v_add_f32_e32 v98, v98, v155
	v_add_f32_e32 v99, v99, v245
	v_lshlrev_b32_e32 v254, 16, v246
	v_and_b32_e32 v246, 0xffff0000, v246
	v_lshlrev_b32_e32 v155, 16, v247
	v_and_b32_e32 v247, 0xffff0000, v247
	v_add_f32_e32 v92, v92, v254
	v_add_f32_e32 v93, v93, v246
	v_add_f32_e32 v94, v94, v155
	v_add_f32_e32 v95, v95, v247
	v_lshlrev_b32_e32 v254, 16, v248
	v_and_b32_e32 v248, 0xffff0000, v248
	v_lshlrev_b32_e32 v155, 16, v249
	v_and_b32_e32 v249, 0xffff0000, v249
	v_add_f32_e32 v88, v88, v254
	v_add_f32_e32 v89, v89, v248
	v_add_f32_e32 v90, v90, v155
	v_add_f32_e32 v91, v91, v249
	v_lshlrev_b32_e32 v254, 16, v250
	v_and_b32_e32 v250, 0xffff0000, v250
	v_lshlrev_b32_e32 v155, 16, v251
	v_and_b32_e32 v251, 0xffff0000, v251
	v_add_f32_e32 v84, v84, v254
	v_add_f32_e32 v85, v85, v250
	v_add_f32_e32 v86, v86, v155
	v_add_f32_e32 v87, v87, v251

.LBB0_238:
	s_waitcnt vmcnt(0)
	s_add_i32 s48, s4, 1
	s_cmp_lt_i32 s48, s0
	s_cselect_b64 s[74:75], -1, 0
	s_cmp_ge_i32 s48, s0
	s_cselect_b64 s[62:63], -1, 0
	s_and_b64 vcc, exec, s[62:63]
	s_cbranch_vccnz .LBB0_252
	s_mov_b64 s[56:57], s[76:77]
	s_lshl_b32 s72, s10, 6
	s_add_i32 s72, s72, s14
	s_add_i32 s11, s72, 3
	s_min_i32 s11, s11, 0x1ff
	s_mov_b32 s37, s11
.LBB0_240:
	s_add_i32 s2, s72, s11
	s_add_i32 s2, s2, 1
	s_ashr_i32 s2, s2, 1
	s_lshl_b32 s15, s2, 2
	s_add_i32 s15, s15, 0
	s_add_i32 s15, s15, 0x21800
	v_mov_b32_e32 v84, s15
	ds_read_b32 v84, v84
	s_add_i32 s15, s2, -1
	s_waitcnt lgkmcnt(0)
	v_readfirstlane_b32 s50, v84
	s_cmp_gt_i32 s50, s48
	s_cselect_b32 s11, s15, s11
	s_cselect_b32 s72, s72, s2
	s_cmp_lt_i32 s72, s11
	s_cbranch_scc1 .LBB0_240
	s_cmp_lg_u32 s72, s37
	s_cbranch_scc1 .Lsel_d1
	s_cmpk_eq_i32 s37, 0x1ff
	s_cbranch_scc1 .Lsel_d1
	s_movk_i32 s11, 0x1ff
	s_movk_i32 s37, 0x1ff
	s_branch .LBB0_240
.Lsel_d1:
	s_mov_b32 s32, s72
	s_lshl_b32 s2, s72, 2
	s_add_i32 s2, s2, 0
	s_add_i32 s11, s2, 0x21800
	s_ashr_i32 s66, s72, 6
	s_and_b32 s50, s72, 63
	v_mov_b32_e32 v84, s11
	s_add_i32 s2, s2, 0x22010
	v_mov_b32_e32 v85, s2
	ds_read_b32 v84, v84
	ds_read_b32 v235, v85
	s_cmp_lg_u32 s66, s10
	s_cselect_b64 s[68:69], -1, 0
	s_cmp_lg_u32 s50, s14
	s_cselect_b64 s[76:77], -1, 0
	s_or_b64 s[88:89], s[68:69], s[76:77]
	s_andn2_b64 vcc, exec, s[88:89]
	s_cbranch_vccnz .LBB0_243
	s_ashr_i32 s73, s72, 31
	s_lshl_b64 s[68:69], s[72:73], 16
	s_add_u32 s68, s43, s68
	s_addc_u32 s69, s47, s69
	s_ashr_i32 s67, s66, 31
	s_lshl_b64 s[72:73], s[66:67], 22
	s_add_u32 s2, s35, s72
	s_addc_u32 s11, s39, s73
	s_lshl_b32 s15, s50, 16
	s_add_u32 s72, s2, s15
	s_addc_u32 s73, s11, 0
	s_waitcnt vmcnt(11)
	v_lshl_add_u64 v[32:33], s[72:73], 0, v[168:169]
	s_waitcnt vmcnt(10)
	v_lshl_add_u64 v[36:37], s[68:69], 0, v[168:169]
	s_waitcnt vmcnt(9)
	v_lshl_add_u64 v[40:41], s[72:73], 0, v[170:171]
	s_waitcnt vmcnt(8)
	v_lshl_add_u64 v[44:45], s[68:69], 0, v[170:171]
	s_waitcnt vmcnt(7)
	v_lshl_add_u64 v[48:49], s[72:73], 0, v[172:173]
	s_waitcnt vmcnt(6)
	v_lshl_add_u64 v[52:53], s[68:69], 0, v[172:173]
	s_waitcnt vmcnt(5)
	v_lshl_add_u64 v[60:61], s[72:73], 0, v[174:175]
	s_waitcnt vmcnt(4)
	v_lshl_add_u64 v[64:65], s[68:69], 0, v[174:175]
	s_waitcnt vmcnt(3)
	v_lshl_add_u64 v[68:69], s[72:73], 0, v[176:177]
	s_waitcnt vmcnt(2)
	v_lshl_add_u64 v[72:73], s[72:73], 0, v[178:179]
	s_waitcnt vmcnt(1)
	v_lshl_add_u64 v[76:77], s[72:73], 0, v[180:181]
	s_waitcnt vmcnt(0)
	v_lshl_add_u64 v[80:81], s[72:73], 0, v[182:183]
	global_load_dwordx4 v[32:35], v[32:33], off
	s_nop 0
	global_load_dwordx4 v[36:39], v[36:37], off
	s_nop 0
	global_load_dwordx4 v[40:43], v[40:41], off
	s_nop 0
	global_load_dwordx4 v[44:47], v[44:45], off
	s_nop 0
	global_load_dwordx4 v[48:51], v[48:49], off
	s_nop 0
	global_load_dwordx4 v[52:55], v[52:53], off
	s_nop 0
	global_load_dwordx4 v[60:63], v[60:61], off
	s_nop 0
	global_load_dwordx4 v[64:67], v[64:65], off
	s_nop 0
	global_load_dwordx4 v[68:71], v[68:69], off
	s_nop 0
	global_load_dwordx4 v[72:75], v[72:73], off
	s_nop 0
	global_load_dwordx4 v[76:79], v[76:77], off
	s_nop 0
	global_load_dwordx4 v[80:83], v[80:81], off
.LBB0_243:
	s_add_i32 s11, s4, 2
	s_mov_b64 s[76:77], s[56:57]
	v_readlane_b32 s56, v255, 18
	v_mov_b32_e32 v236, -1
	s_cmp_ge_i32 s11, s0
	v_mov_b32_e32 v237, -1
	v_readlane_b32 s57, v255, 19
	s_cbranch_scc1 .LBB0_251
	s_mov_b32 s51, s32
	s_add_i32 s65, s32, 3
	s_min_i32 s65, s65, 0x1ff
	s_mov_b32 s37, s65
.LBB0_245:
	s_add_i32 s2, s51, s65
	s_add_i32 s2, s2, 1
	s_ashr_i32 s2, s2, 1
	s_lshl_b32 s15, s2, 2
	s_add_i32 s15, s15, 0
	s_add_i32 s15, s15, 0x21800
	v_mov_b32_e32 v85, s15
	ds_read_b32 v85, v85
	s_add_i32 s15, s2, -1
	s_waitcnt lgkmcnt(0)
	v_readfirstlane_b32 s67, v85
	s_cmp_gt_i32 s67, s11
	s_cselect_b32 s65, s15, s65
	s_cselect_b32 s51, s51, s2
	s_cmp_lt_i32 s51, s65
	s_cbranch_scc1 .LBB0_245
	s_cmp_lg_u32 s51, s37
	s_cbranch_scc1 .Lsel_d2
	s_cmpk_eq_i32 s37, 0x1ff
	s_cbranch_scc1 .Lsel_d2
	s_movk_i32 s65, 0x1ff
	s_movk_i32 s37, 0x1ff
	s_branch .LBB0_245
.Lsel_d2:
	s_lshl_b32 s15, s51, 2
	s_add_i32 s15, s15, 0
	s_add_i32 s65, s15, 0x21800
	v_mov_b32_e32 v85, s65
	ds_read_b32 v86, v85
	s_lshr_b32 s2, s51, 6
	s_and_b32 s51, s51, 63
	s_add_i32 s15, s15, 0x22010
	v_mov_b32_e32 v85, s15
	s_add_i32 s15, s51, -1
	s_mul_i32 s15, s15, s51
	s_waitcnt lgkmcnt(0)
	v_sub_u32_e32 v86, s11, v86
	s_mul_i32 s11, s51, 63
	s_lshr_b32 s51, s15, 31
	s_add_i32 s15, s15, s51
	s_sext_i32_i16 s15, s15
	ds_read_b32 v85, v85
	s_lshr_b32 s15, s15, 1
	s_sub_i32 s15, 0, s15
	s_sext_i32_i16 s15, s15
	s_add_i32 s11, s11, s15
	v_lshl_add_u32 v86, v86, 8, v190
	s_mul_i32 s2, s2, 0x7e000
	s_lshl_b32 s11, s11, 8
	s_add_i32 s11, s11, s2
	s_waitcnt lgkmcnt(0)
	v_cmp_lt_i32_e32 vcc, v86, v85
	v_mov_b32_e32 v237, -1
	v_mov_b32_e32 v236, -1
	s_and_saveexec_b64 s[72:73], vcc
	s_cbranch_execz .LBB0_248
	v_add_u32_e32 v88, s11, v86
	v_ashrrev_i32_e32 v89, 31, v88
	v_lshl_add_u64 v[88:89], v[88:89], 2, s[8:9]
	global_load_dword v236, v[88:89], off
.LBB0_248:
	s_or_b64 exec, exec, s[72:73]
	v_or_b32_e32 v86, 16, v86
	v_cmp_lt_i32_e32 vcc, v86, v85
	s_and_saveexec_b64 s[72:73], vcc
	s_mov_b32 s65, 0x7e000
	s_cbranch_execz .LBB0_250
	v_add_u32_e32 v86, s11, v86
	v_ashrrev_i32_e32 v87, 31, v86
	v_lshl_add_u64 v[86:87], v[86:87], 2, s[8:9]
	global_load_dword v237, v[86:87], off

.LBB0_255:
	v_add_u32_e32 v241, v239, v166
	ds_read_b128 v[148:151], v241
	ds_read_b128 v[152:155], v241 offset:1088
	ds_read_b128 v[250:253], v241 offset:64
	ds_read_b128 v[202:205], v241 offset:1152
	v_add_u32_e32 v240, v158, v166
	s_add_i32 s11, s11, -2
	s_waitcnt lgkmcnt(3)
	v_mfma_f32_16x16x32_bf16 v[242:245], v[148:151], v[0:3], v[56:59]
	v_add_u32_e32 v239, 0x4400, v239
	v_add_u32_e32 v158, 0x80, v158
	s_cmp_lg_u32 s11, 0
	s_waitcnt lgkmcnt(2)
	v_mfma_f32_16x16x32_bf16 v[246:249], v[152:155], v[0:3], v[56:59]
	v_mfma_f32_16x16x32_bf16 v[148:151], v[148:151], v[16:19], v[56:59]
	v_mfma_f32_16x16x32_bf16 v[152:155], v[152:155], v[16:19], v[56:59]
	s_waitcnt lgkmcnt(1)
	v_mfma_f32_16x16x32_bf16 v[242:245], v[250:253], v[4:7], v[242:245]
	s_waitcnt lgkmcnt(0)
	v_mfma_f32_16x16x32_bf16 v[246:249], v[202:205], v[4:7], v[246:249]
	v_mfma_f32_16x16x32_bf16 v[148:151], v[250:253], v[20:23], v[148:151]
	v_mfma_f32_16x16x32_bf16 v[152:155], v[202:205], v[20:23], v[152:155]
	ds_read_b128 v[202:205], v241 offset:128
	ds_read_b128 v[250:253], v241 offset:1216
	s_waitcnt lgkmcnt(1)
	v_mfma_f32_16x16x32_bf16 v[242:245], v[202:205], v[8:11], v[242:245]
	s_waitcnt lgkmcnt(0)
	v_mfma_f32_16x16x32_bf16 v[246:249], v[250:253], v[8:11], v[246:249]
	v_mfma_f32_16x16x32_bf16 v[148:151], v[202:205], v[24:27], v[148:151]
	v_mfma_f32_16x16x32_bf16 v[152:155], v[250:253], v[24:27], v[152:155]
	ds_read_b128 v[202:205], v241 offset:192
	ds_read_b128 v[250:253], v241 offset:1280
	s_waitcnt lgkmcnt(1)
	v_mfma_f32_16x16x32_bf16 v[242:245], v[202:205], v[12:15], v[242:245]
	v_mfma_f32_16x16x32_bf16 v[148:151], v[202:205], v[28:31], v[148:151]
	s_nop 5
	v_exp_f32_e32 v202, v242
	v_exp_f32_e32 v242, v243
	v_exp_f32_e32 v244, v244
	s_waitcnt lgkmcnt(0)
	v_mfma_f32_16x16x32_bf16 v[246:249], v[250:253], v[12:15], v[246:249]
	v_mfma_f32_16x16x32_bf16 v[152:155], v[250:253], v[28:31], v[152:155]
	v_exp_f32_e32 v203, v148
	v_exp_f32_e32 v243, v149
	v_exp_f32_e32 v250, v245
	v_exp_f32_e32 v245, v150
	v_exp_f32_e32 v251, v151
	s_nop 1
	v_exp_f32_e32 v204, v246
	v_exp_f32_e32 v205, v152
	v_pk_add_f32 v[148:149], v[188:189], v[202:203]
	v_exp_f32_e32 v246, v247
	v_exp_f32_e32 v247, v153
	v_pk_add_f32 v[148:149], v[242:243], v[148:149]
	v_exp_f32_e32 v248, v248
	v_exp_f32_e32 v252, v249
	v_exp_f32_e32 v249, v154
	v_pk_add_f32 v[148:149], v[244:245], v[148:149]
	v_exp_f32_e32 v253, v155
	v_pk_add_f32 v[148:149], v[250:251], v[148:149]
	s_nop 0
	v_pk_add_f32 v[148:149], v[204:205], v[148:149]
	s_nop 0
	v_pk_add_f32 v[148:149], v[246:247], v[148:149]
	s_nop 0
	v_pk_add_f32 v[152:153], v[248:249], v[148:149]
	v_cvt_pk_bf16_f32 v148, v202, v242
	v_add_u32_e32 v202, 0x11000, v240
	v_cvt_pk_bf16_f32 v149, v244, v250
	v_cvt_pk_bf16_f32 v150, v204, v246
	v_cvt_pk_bf16_f32 v151, v248, v252
	v_pk_add_f32 v[188:189], v[252:253], v[152:153]
	v_cvt_pk_bf16_f32 v152, v203, v243
	v_cvt_pk_bf16_f32 v153, v245, v251
	v_cvt_pk_bf16_f32 v154, v205, v247
	v_cvt_pk_bf16_f32 v155, v249, v253
	ds_read_b128 v[202:205], v202
	s_waitcnt lgkmcnt(0)
	v_mfma_f32_16x16x32_bf16 v[144:147], v[202:205], v[148:151], v[144:147]
	v_mfma_f32_16x16x32_bf16 v[124:127], v[202:205], v[152:155], v[124:127]
	v_add_u32_e32 v202, 0x13100, v240
	ds_read_b128 v[202:205], v202
	s_waitcnt lgkmcnt(0)
	v_mfma_f32_16x16x32_bf16 v[140:143], v[202:205], v[148:151], v[140:143]
	v_mfma_f32_16x16x32_bf16 v[112:115], v[202:205], v[152:155], v[112:115]
	v_add_u32_e32 v202, 0x15200, v240
	ds_read_b128 v[202:205], v202
	s_waitcnt lgkmcnt(0)
	v_mfma_f32_16x16x32_bf16 v[136:139], v[202:205], v[148:151], v[136:139]
	v_mfma_f32_16x16x32_bf16 v[108:111], v[202:205], v[152:155], v[108:111]
	v_add_u32_e32 v202, 0x17300, v240
	ds_read_b128 v[202:205], v202
	s_waitcnt lgkmcnt(0)
	v_mfma_f32_16x16x32_bf16 v[132:135], v[202:205], v[148:151], v[132:135]
	v_mfma_f32_16x16x32_bf16 v[100:103], v[202:205], v[152:155], v[100:103]
	v_add_u32_e32 v202, 0x19400, v240
	ds_read_b128 v[202:205], v202
	s_waitcnt lgkmcnt(0)
	v_mfma_f32_16x16x32_bf16 v[128:131], v[202:205], v[148:151], v[128:131]
	v_mfma_f32_16x16x32_bf16 v[96:99], v[202:205], v[152:155], v[96:99]
	v_add_u32_e32 v202, 0x1b500, v240
	ds_read_b128 v[202:205], v202
	s_waitcnt lgkmcnt(0)
	v_mfma_f32_16x16x32_bf16 v[120:123], v[202:205], v[148:151], v[120:123]
	v_mfma_f32_16x16x32_bf16 v[92:95], v[202:205], v[152:155], v[92:95]
	v_add_u32_e32 v202, 0x1d600, v240
	ds_read_b128 v[202:205], v202
	s_waitcnt lgkmcnt(0)
	v_mfma_f32_16x16x32_bf16 v[116:119], v[202:205], v[148:151], v[116:119]
	v_mfma_f32_16x16x32_bf16 v[88:91], v[202:205], v[152:155], v[88:91]
	v_add_u32_e32 v202, 0x1f700, v240
	ds_read_b128 v[202:205], v202
	s_waitcnt lgkmcnt(0)
	v_mfma_f32_16x16x32_bf16 v[104:107], v[202:205], v[148:151], v[104:107]
	v_mfma_f32_16x16x32_bf16 v[84:87], v[202:205], v[152:155], v[84:87]
	ds_read_b128 v[148:151], v241 offset:8704
	ds_read_b128 v[152:155], v241 offset:9792
	ds_read_b128 v[246:249], v241 offset:8768
	ds_read_b128 v[250:253], v241 offset:9856
	s_waitcnt lgkmcnt(3)
	v_mfma_f32_16x16x32_bf16 v[202:205], v[148:151], v[0:3], v[56:59]
	s_waitcnt lgkmcnt(2)
	v_mfma_f32_16x16x32_bf16 v[242:245], v[152:155], v[0:3], v[56:59]
	v_mfma_f32_16x16x32_bf16 v[148:151], v[148:151], v[16:19], v[56:59]
	v_mfma_f32_16x16x32_bf16 v[152:155], v[152:155], v[16:19], v[56:59]
	s_waitcnt lgkmcnt(1)
	v_mfma_f32_16x16x32_bf16 v[202:205], v[246:249], v[4:7], v[202:205]
	s_waitcnt lgkmcnt(0)
	v_mfma_f32_16x16x32_bf16 v[242:245], v[250:253], v[4:7], v[242:245]
	v_mfma_f32_16x16x32_bf16 v[148:151], v[246:249], v[20:23], v[148:151]
	v_mfma_f32_16x16x32_bf16 v[152:155], v[250:253], v[20:23], v[152:155]
	ds_read_b128 v[246:249], v241 offset:8832
	ds_read_b128 v[250:253], v241 offset:9920
	s_waitcnt lgkmcnt(1)
	v_mfma_f32_16x16x32_bf16 v[202:205], v[246:249], v[8:11], v[202:205]
	s_waitcnt lgkmcnt(0)
	v_mfma_f32_16x16x32_bf16 v[242:245], v[250:253], v[8:11], v[242:245]
	v_mfma_f32_16x16x32_bf16 v[148:151], v[246:249], v[24:27], v[148:151]
	v_mfma_f32_16x16x32_bf16 v[152:155], v[250:253], v[24:27], v[152:155]
	ds_read_b128 v[246:249], v241 offset:8896
	ds_read_b128 v[250:253], v241 offset:9984
	s_waitcnt lgkmcnt(1)
	v_mfma_f32_16x16x32_bf16 v[202:205], v[246:249], v[12:15], v[202:205]
	v_mfma_f32_16x16x32_bf16 v[148:151], v[246:249], v[28:31], v[148:151]
	s_nop 6
	v_exp_f32_e32 v202, v202
	v_exp_f32_e32 v246, v203
	v_exp_f32_e32 v204, v204
	s_waitcnt lgkmcnt(0)
	v_mfma_f32_16x16x32_bf16 v[242:245], v[250:253], v[12:15], v[242:245]
	v_mfma_f32_16x16x32_bf16 v[152:155], v[250:253], v[28:31], v[152:155]
	v_exp_f32_e32 v203, v148
	v_exp_f32_e32 v247, v149
	v_exp_f32_e32 v250, v205
	v_exp_f32_e32 v205, v150
	v_exp_f32_e32 v251, v151
	s_nop 1
	v_exp_f32_e32 v242, v242
	v_exp_f32_e32 v248, v243
	v_exp_f32_e32 v243, v152
	v_pk_add_f32 v[148:149], v[188:189], v[202:203]
	v_exp_f32_e32 v249, v153
	v_pk_add_f32 v[148:149], v[246:247], v[148:149]
	v_exp_f32_e32 v244, v244
	v_exp_f32_e32 v252, v245
	v_exp_f32_e32 v245, v154
	v_pk_add_f32 v[148:149], v[204:205], v[148:149]
	v_exp_f32_e32 v253, v155
	v_pk_add_f32 v[148:149], v[250:251], v[148:149]
	s_nop 0
	v_pk_add_f32 v[148:149], v[242:243], v[148:149]
	s_nop 0
	v_pk_add_f32 v[148:149], v[248:249], v[148:149]
	s_nop 0
	v_pk_add_f32 v[152:153], v[244:245], v[148:149]
	v_cvt_pk_bf16_f32 v148, v202, v246
	v_add_u32_e32 v202, 0x11040, v240
	v_cvt_pk_bf16_f32 v149, v204, v250
	v_cvt_pk_bf16_f32 v150, v242, v248
	v_cvt_pk_bf16_f32 v151, v244, v252
	v_pk_add_f32 v[188:189], v[252:253], v[152:153]
	v_cvt_pk_bf16_f32 v152, v203, v247
	v_cvt_pk_bf16_f32 v153, v205, v251
	v_cvt_pk_bf16_f32 v154, v243, v249
	v_cvt_pk_bf16_f32 v155, v245, v253
	ds_read_b128 v[202:205], v202
	s_waitcnt lgkmcnt(0)
	v_mfma_f32_16x16x32_bf16 v[144:147], v[202:205], v[148:151], v[144:147]
	v_mfma_f32_16x16x32_bf16 v[124:127], v[202:205], v[152:155], v[124:127]
	v_add_u32_e32 v202, 0x13140, v240
	ds_read_b128 v[202:205], v202
	s_waitcnt lgkmcnt(0)
	v_mfma_f32_16x16x32_bf16 v[140:143], v[202:205], v[148:151], v[140:143]
	v_mfma_f32_16x16x32_bf16 v[112:115], v[202:205], v[152:155], v[112:115]
	v_add_u32_e32 v202, 0x15240, v240
	ds_read_b128 v[202:205], v202
	s_waitcnt lgkmcnt(0)
	v_mfma_f32_16x16x32_bf16 v[136:139], v[202:205], v[148:151], v[136:139]
	v_mfma_f32_16x16x32_bf16 v[108:111], v[202:205], v[152:155], v[108:111]
	v_add_u32_e32 v202, 0x17340, v240
	ds_read_b128 v[202:205], v202
	s_waitcnt lgkmcnt(0)
	v_mfma_f32_16x16x32_bf16 v[132:135], v[202:205], v[148:151], v[132:135]
	v_mfma_f32_16x16x32_bf16 v[100:103], v[202:205], v[152:155], v[100:103]
	v_add_u32_e32 v202, 0x19440, v240
	ds_read_b128 v[202:205], v202
	s_waitcnt lgkmcnt(0)
	v_mfma_f32_16x16x32_bf16 v[128:131], v[202:205], v[148:151], v[128:131]
	v_mfma_f32_16x16x32_bf16 v[96:99], v[202:205], v[152:155], v[96:99]
	v_add_u32_e32 v202, 0x1b540, v240
	ds_read_b128 v[202:205], v202
	s_waitcnt lgkmcnt(0)
	v_mfma_f32_16x16x32_bf16 v[120:123], v[202:205], v[148:151], v[120:123]
	v_mfma_f32_16x16x32_bf16 v[92:95], v[202:205], v[152:155], v[92:95]
	v_add_u32_e32 v202, 0x1d640, v240
	ds_read_b128 v[202:205], v202
	s_waitcnt lgkmcnt(0)
	v_mfma_f32_16x16x32_bf16 v[116:119], v[202:205], v[148:151], v[116:119]
	v_mfma_f32_16x16x32_bf16 v[88:91], v[202:205], v[152:155], v[88:91]
	v_add_u32_e32 v202, 0x1f740, v240
	ds_read_b128 v[202:205], v202
	s_waitcnt lgkmcnt(0)
	v_mfma_f32_16x16x32_bf16 v[104:107], v[202:205], v[148:151], v[104:107]
	v_mfma_f32_16x16x32_bf16 v[84:87], v[202:205], v[152:155], v[84:87]
	s_cbranch_scc1 .LBB0_255
.LBB0_256:
	s_or_b64 exec, exec, s[72:73]
	s_andn2_b64 vcc, exec, s[74:75]
	s_cbranch_vccnz .LBB0_258
	s_ashr_i32 s67, s66, 31
	v_bfe_u32 v158, v217, 2, 29
	s_lshl_b64 s[68:69], s[66:67], 22
	s_waitcnt vmcnt(7)
	v_lshlrev_b64 v[0:1], 8, v[158:159]
	v_bfe_u32 v158, v216, 2, 29
	s_waitcnt vmcnt(3)
	v_lshl_add_u64 v[16:17], v[184:185], 0, s[68:69]
	v_lshlrev_b64 v[18:19], 8, v[158:159]
	v_lshl_add_u64 v[12:13], v[16:17], 0, v[0:1]
	s_waitcnt vmcnt(0)
	v_cmp_ne_u32_e32 vcc, -1, v236
	v_or_b32_e32 v148, 0x80000000, v236
	v_cmp_ne_u32_e64 s[68:69], -1, v237
	v_or_b32_e32 v149, 0x80000000, v237
	v_cndmask_b32_e32 v236, 0, v148, vcc
	v_cndmask_b32_e64 v237, 0, v149, s[68:69]
	v_lshl_add_u64 v[28:29], v[16:17], 0, v[18:19]
	global_load_dwordx4 v[0:3], v[12:13], off
	global_load_dwordx4 v[4:7], v[12:13], off offset:64
	global_load_dwordx4 v[8:11], v[12:13], off offset:128
	s_nop 0
	global_load_dwordx4 v[12:15], v[12:13], off offset:192
	s_nop 0
	global_load_dwordx4 v[16:19], v[28:29], off
	global_load_dwordx4 v[20:23], v[28:29], off offset:64
	global_load_dwordx4 v[24:27], v[28:29], off offset:128
	s_nop 0
	global_load_dwordx4 v[28:31], v[28:29], off offset:192
.LBB0_258:
	v_and_b32_e32 v149, 64, v197
	v_xor_b32_e32 v148, 16, v197
	v_add_u32_e32 v149, 64, v149
	v_cmp_lt_i32_e32 vcc, v148, v149
	v_xor_b32_e32 v150, 32, v197
	s_ashr_i32 s11, s10, 31
	v_cndmask_b32_e32 v148, v197, v148, vcc
	v_lshlrev_b32_e32 v151, 2, v148
	ds_bpermute_b32 v148, v151, v188
	v_cmp_lt_i32_e32 vcc, v150, v149
	s_lshl_b64 s[68:69], s[10:11], 8
	s_waitcnt lgkmcnt(0)
	v_add_f32_e32 v153, v188, v148
	v_cndmask_b32_e32 v149, v197, v150, vcc
	v_lshlrev_b32_e32 v152, 2, v149
	ds_bpermute_b32 v154, v152, v153
	v_lshl_add_u64 v[148:149], v[186:187], 0, s[68:69]
	v_cmp_gt_i32_e32 vcc, 0, v214
	s_and_saveexec_b64 s[72:73], vcc
	s_cbranch_execz .LBB0_261
	v_bfe_u32 v155, v214, 2, 29
	v_and_b32_e32 v150, 3, v214
	v_mad_u64_u32 v[202:203], s[68:69], v155, 3, v[150:151]
	v_mov_b32_e32 v203, v159
	v_lshlrev_b64 v[202:203], 11, v[202:203]
	v_lshl_add_u64 v[202:203], v[148:149], 0, v[202:203]
	v_and_b32_e32 v204, 16, v197
	v_lshrrev_b32_e32 v205, 1, v204
	v_add_u32_e32 v204, v204, v205
	v_add_co_u32_e32 v202, vcc, v202, v204
	s_nop 1
	v_addc_co_u32_e32 v203, vcc, 0, v203, vcc
	v_cvt_pk_bf16_f32 v144, v144, v145
	v_cvt_pk_bf16_f32 v145, v146, v147
	v_cvt_pk_bf16_f32 v146, v140, v141
	v_cvt_pk_bf16_f32 v147, v142, v143
	v_cvt_pk_bf16_f32 v136, v136, v137
	v_cvt_pk_bf16_f32 v137, v138, v139
	v_cvt_pk_bf16_f32 v138, v132, v133
	v_cvt_pk_bf16_f32 v139, v134, v135
	v_cvt_pk_bf16_f32 v128, v128, v129
	v_cvt_pk_bf16_f32 v129, v130, v131
	v_cvt_pk_bf16_f32 v130, v120, v121
	v_cvt_pk_bf16_f32 v131, v122, v123
	v_cvt_pk_bf16_f32 v116, v116, v117
	v_cvt_pk_bf16_f32 v117, v118, v119
	v_cvt_pk_bf16_f32 v118, v104, v105
	v_cvt_pk_bf16_f32 v119, v106, v107
	s_nop 1
	v_permlane16_swap_b32_e32 v144, v146
	v_permlane16_swap_b32_e32 v145, v147
	v_permlane16_swap_b32_e32 v136, v138
	v_permlane16_swap_b32_e32 v137, v139
	v_permlane16_swap_b32_e32 v128, v130
	v_permlane16_swap_b32_e32 v129, v131
	v_permlane16_swap_b32_e32 v116, v118
	v_permlane16_swap_b32_e32 v117, v119
	global_store_dwordx4 v[202:203], v[144:147], off
	global_store_dwordx4 v[202:203], v[136:139], off offset:64
	global_store_dwordx4 v[202:203], v[128:131], off offset:128
	global_store_dwordx4 v[202:203], v[116:119], off offset:192
	s_and_b64 exec, exec, s[6:7]
	s_cbranch_execz .LBB0_261
	v_lshlrev_b32_e32 v158, 3, v155
	v_lshl_add_u64 v[104:105], v[158:159], 0, s[10:11]
	v_mad_u64_u32 v[106:107], s[68:69], v104, 12, s[24:25]
	v_mad_i32_i24 v107, v105, 12, v107
	v_lshlrev_b32_e32 v158, 2, v150
	s_waitcnt lgkmcnt(0)
	v_add_f32_e32 v116, v153, v154
	v_lshl_add_u64 v[104:105], v[106:107], 0, v[158:159]
	global_store_dword v[104:105], v116, off
.LBB0_261:
	s_or_b64 exec, exec, s[72:73]
	ds_bpermute_b32 v104, v151, v189
	v_cmp_gt_i32_e32 vcc, 0, v215
	s_waitcnt lgkmcnt(0)
	v_add_f32_e32 v105, v189, v104
	ds_bpermute_b32 v106, v152, v105
	s_and_saveexec_b64 s[72:73], vcc
	s_cbranch_execz .LBB0_264
	v_bfe_u32 v107, v215, 2, 29
	v_and_b32_e32 v104, 3, v215
	v_mad_u64_u32 v[116:117], s[68:69], v107, 3, v[104:105]
	v_mov_b32_e32 v117, v159
	v_lshlrev_b64 v[116:117], 11, v[116:117]
	v_lshl_add_u64 v[116:117], v[148:149], 0, v[116:117]
	v_and_b32_e32 v118, 16, v197
	v_lshrrev_b32_e32 v119, 1, v118
	v_add_u32_e32 v118, v118, v119
	v_add_co_u32_e32 v116, vcc, v116, v118
	s_nop 1
	v_addc_co_u32_e32 v117, vcc, 0, v117, vcc
	v_cvt_pk_bf16_f32 v124, v124, v125
	v_cvt_pk_bf16_f32 v125, v126, v127
	v_cvt_pk_bf16_f32 v126, v112, v113
	v_cvt_pk_bf16_f32 v127, v114, v115
	v_cvt_pk_bf16_f32 v108, v108, v109
	v_cvt_pk_bf16_f32 v109, v110, v111
	v_cvt_pk_bf16_f32 v110, v100, v101
	v_cvt_pk_bf16_f32 v111, v102, v103
	v_cvt_pk_bf16_f32 v96, v96, v97
	v_cvt_pk_bf16_f32 v97, v98, v99
	v_cvt_pk_bf16_f32 v98, v92, v93
	v_cvt_pk_bf16_f32 v99, v94, v95
	v_cvt_pk_bf16_f32 v88, v88, v89
	v_cvt_pk_bf16_f32 v89, v90, v91
	v_cvt_pk_bf16_f32 v90, v84, v85
	v_cvt_pk_bf16_f32 v91, v86, v87
	s_nop 1
	v_permlane16_swap_b32_e32 v124, v126
	v_permlane16_swap_b32_e32 v125, v127
	v_permlane16_swap_b32_e32 v108, v110
	v_permlane16_swap_b32_e32 v109, v111
	v_permlane16_swap_b32_e32 v96, v98
	v_permlane16_swap_b32_e32 v97, v99
	v_permlane16_swap_b32_e32 v88, v90
	v_permlane16_swap_b32_e32 v89, v91
	global_store_dwordx4 v[116:117], v[124:127], off
	global_store_dwordx4 v[116:117], v[108:111], off offset:64
	global_store_dwordx4 v[116:117], v[96:99], off offset:128
	global_store_dwordx4 v[116:117], v[88:91], off offset:192
	s_and_b64 exec, exec, s[6:7]
	s_cbranch_execz .LBB0_264
	v_lshlrev_b32_e32 v158, 3, v107
	v_lshl_add_u64 v[84:85], v[158:159], 0, s[10:11]
	v_mad_u64_u32 v[86:87], s[68:69], v84, 12, s[24:25]
	v_mad_i32_i24 v87, v85, 12, v87
	v_lshlrev_b32_e32 v158, 2, v104
	s_waitcnt lgkmcnt(0)
	v_add_f32_e32 v88, v105, v106
	v_lshl_add_u64 v[84:85], v[86:87], 0, v[158:159]
	global_store_dword v[84:85], v88, off
